# v52 plus a ~12 us start stagger of the even-XCD six-unit workgroups in GEMM1 (they carry the light epilogue mix) so epilogue store bursts of the two XCD halves interleave
# baseline (speedup 1.0000x reference)
.LBB0_246:
	s_ashr_i32 s52, s46, 31
	s_ashr_i32 s58, s47, 31
	s_add_u32 s0, s96, 0x8b00000
	s_addc_u32 s1, s97, 0
	s_add_u32 s88, s96, 0x31238800
	s_addc_u32 s89, s97, 0
	s_add_u32 s4, s96, 0x34238800
	s_addc_u32 s5, s97, 0
	v_writelane_b32 v252, s4, 56
	s_add_u32 s74, s96, 0x35238800
	s_addc_u32 s75, s97, 0
	v_writelane_b32 v252, s5, 57
	s_andn2_b64 vcc, exec, s[2:3]
	v_writelane_b32 v252, s56, 58
	s_nop 1
	v_writelane_b32 v252, s57, 59
	s_cbranch_vccnz .LBB0_625
	s_waitcnt vmcnt(2)
	v_ashrrev_i32_e32 v1, 31, v8
	v_lshrrev_b32_e32 v1, 26, v1
	v_add_u32_e32 v1, v8, v1
	v_ashrrev_i32_e32 v9, 6, v1
	v_bfe_i32 v1, v8, 27, 1
	v_lshlrev_b32_e32 v0, 4, v8
	v_lshrrev_b32_e32 v1, 22, v1
	v_add_u32_e32 v1, v0, v1
	v_and_b32_e32 v1, 0xfffffc00, v1
	v_sub_u32_e32 v1, v0, v1
	v_lshrrev_b32_e32 v2, 4, v1
	v_bitop3_b32 v2, v2, v1, 32 bitop3:0x6c
	v_ashrrev_i32_e32 v1, 31, v1
	v_lshrrev_b32_e32 v1, 26, v1
	v_add_u32_e32 v1, v2, v1
	v_ashrrev_i32_e32 v10, 6, v1
	v_lshlrev_b32_e32 v3, 3, v9
	s_waitcnt vmcnt(0)
	v_mul_i32_i24_e32 v4, 64, v10
	v_and_b32_e32 v3, -16, v3
	v_sub_u32_e32 v2, v2, v4
	v_mov_b32_e32 v4, 1
	v_add_u32_e32 v1, v10, v3
	v_lshlrev_b32_e32 v3, 5, v9
	v_ashrrev_i16_sdwa v2, v4, sext(v2) dst_sel:DWORD dst_unused:UNUSED_PAD src0_sel:DWORD src1_sel:BYTE_0
	v_and_b32_e32 v3, 32, v3
	v_bfe_i32 v11, v2, 0, 16
	v_and_b32_e32 v6, 3, v10
	s_mov_b32 s3, 0xfffe0
	v_add_lshl_u32 v3, v3, v11, 1
	v_add_u32_e32 v0, 0x2000, v0
	v_lshlrev_b32_e32 v2, 1, v1
	v_lshrrev_b32_e32 v5, 2, v1
	v_and_or_b32 v6, v1, s3, v6
	v_lshl_add_u32 v148, v1, 12, v3
	v_ashrrev_i32_e32 v1, 31, v0
	v_lshrrev_b32_e32 v1, 22, v1
	v_add_u32_e32 v1, v0, v1
	v_ashrrev_i32_e32 v12, 10, v1
	v_mul_i32_i24_e32 v1, 0x400, v12
	v_sub_u32_e32 v0, v0, v1
	v_and_b32_e32 v2, 24, v2
	v_and_b32_e32 v5, 4, v5
	v_lshrrev_b32_e32 v1, 4, v0
	v_or3_b32 v2, v6, v5, v2
	v_bitop3_b32 v0, v1, v0, 32 bitop3:0x6c
	v_lshl_add_u32 v150, v2, 12, v3
	v_ashrrev_i32_e32 v2, 31, v0
	v_lshrrev_b32_e32 v2, 26, v2
	v_add_u32_e32 v2, v0, v2
	v_lshlrev_b32_e32 v1, 3, v12
	v_ashrrev_i32_e32 v13, 6, v2
	v_and_b32_e32 v2, 0xc0, v2
	v_and_b32_e32 v1, -16, v1
	v_sub_u32_e32 v0, v0, v2
	s_ashr_i32 s2, s31, 6
	v_add_u32_e32 v1, v13, v1
	v_ashrrev_i16_sdwa v0, v4, sext(v0) dst_sel:DWORD dst_unused:UNUSED_PAD src0_sel:DWORD src1_sel:BYTE_0
	v_and_b32_e32 v4, 3, v13
	s_ashr_i32 s91, s90, 31
	s_ashr_i32 s83, s82, 31
	v_and_or_b32 v4, v1, s3, v4
	s_ashr_i32 s3, s31, 8
	s_lshl_b32 s33, s2, 10
	s_lshl_b64 s[4:5], s[90:91], 20
	s_lshl_b64 s[6:7], s[82:83], 20
	s_add_u32 s6, s56, s6
	v_lshlrev_b32_e32 v3, 5, v12
	v_bfe_i32 v14, v0, 0, 16
	v_lshlrev_b32_e32 v0, 1, v1
	v_lshrrev_b32_e32 v2, 2, v1
	s_addc_u32 s7, s57, s7
	s_add_i32 s44, s33, 0
	v_and_b32_e32 v3, 32, v3
	v_and_b32_e32 v0, 24, v0
	v_and_b32_e32 v2, 4, v2
	s_bitcmp1_b32 s47, 0
	s_cbranch_scc1 .Lp1_nostagger
	s_cmpk_ge_u32 s47, 0xb4
	s_cbranch_scc1 .Lp1_nostagger
	s_sleep 127
	s_sleep 127
	s_sleep 127
.Lp1_nostagger:
	s_add_i32 m0, s44, 0x10000
	v_or3_b32 v0, v4, v2, v0
	v_add_lshl_u32 v2, v3, v14, 1
	global_load_lds_dwordx4 v150, s[6:7]
	s_add_i32 m0, s44, 0x12000
	v_lshl_add_u32 v154, v0, 12, v2
	s_add_u32 s4, s96, s4
	global_load_lds_dwordx4 v154, s[6:7]
	s_addc_u32 s5, s97, s5
	s_mov_b32 m0, s44
	s_add_i32 s45, s44, 0x2000
	v_lshl_add_u32 v152, v1, 12, v2
	global_load_lds_dwordx4 v148, s[4:5]
	s_mov_b32 m0, s45
	s_add_u32 s8, s6, 0x80000
	global_load_lds_dwordx4 v152, s[4:5]
	s_addc_u32 s9, s7, 0
	s_add_i32 m0, s44, 0x14000
	v_mov_b32_e32 v157, 0
	global_load_lds_dwordx4 v150, s[8:9]
	s_add_i32 m0, s44, 0x16000
	v_mov_b32_e32 v151, v157
	global_load_lds_dwordx4 v154, s[8:9]
	s_add_u32 s8, s4, 0x80000
	s_addc_u32 s9, s5, 0
	s_add_i32 s51, s44, 0x4000
	s_mov_b32 m0, s51
	s_add_i32 s55, s44, 0x6000
	global_load_lds_dwordx4 v148, s[8:9]
	s_mov_b32 m0, s55
	v_mov_b32_e32 v155, v157
	global_load_lds_dwordx4 v152, s[8:9]
	v_mov_b32_e32 v149, v157
	v_mov_b32_e32 v153, v157
	s_movk_i32 s56, 0x2000
	s_mov_b32 s21, 0
	v_lshl_add_u64 v[6:7], s[6:7], 0, v[150:151]
	v_lshl_add_u64 v[4:5], s[6:7], 0, v[154:155]
	v_lshl_add_u64 v[2:3], s[4:5], 0, v[148:149]
	s_cmp_lg_u32 s3, 1
	v_lshl_add_u64 v[0:1], s[4:5], 0, v[152:153]
	s_cbranch_scc1 .LBB0_249
	s_barrier
